# residual epilogue: the two 64-byte halves of each array row requested back to back (hi, hi+64, lo, lo+64) for loads and stores
# speedup vs baseline: 1.0030x; 1.0004x over previous
;     __device__ __forceinline__ void operator()(const f32x4 (&acc)[2][2][4][2], const Unit& u, int wr, int wc, int fr, int fq) const {
;     ...
;                 for (int bj = 0; bj < 2; ++bj) { const size_t c = (size_t)(row0 + ai * HALF + (mh + m) * 16) * 1024 + col0 + bj * 32;
;                     if (xin) { rh[m][bj] = __builtin_bit_cast(u32x4, *(const f32x4*)(xin + c)); rl[m][bj] = __builtin_bit_cast(u32x4, *(const f32x4*)(xin + c + 4)); }
;                     else { rh[m][bj] = *(const u32x4*)(hi + c); rl[m][bj] = *(const u32x4*)(lo_in + c); } }
; #pragma unroll
;             for (int m = 0; m < 2; ++m) { const int r = row0 + ai * HALF + (mh + m) * 16; float s = 0.f;
; #pragma unroll
;                 for (int bj = 0; bj < 2; ++bj) { const size_t c = (size_t)r * 1024 + col0 + bj * 32; const u32x4 h = rh[m][bj], l = rl[m][bj]; f32x4 b0, b1;
;                     if (xin) { b0 = __builtin_bit_cast(f32x4, h); b1 = __builtin_bit_cast(f32x4, l); }
;                     else { b0 = (f32x4){__uint_as_float(h.x << 16) + __uint_as_float(l.x << 16), __uint_as_float(h.x & 0xffff0000u) + __uint_as_float(l.x & 0xffff0000u),
;                                         __uint_as_float(h.y << 16) + __uint_as_float(l.y << 16), __uint_as_float(h.y & 0xffff0000u) + __uint_as_float(l.y & 0xffff0000u)};
;                            b1 = (f32x4){__uint_as_float(h.z << 16) + __uint_as_float(l.z << 16), __uint_as_float(h.z & 0xffff0000u) + __uint_as_float(l.z & 0xffff0000u),
;                                         __uint_as_float(h.w << 16) + __uint_as_float(l.w << 16), __uint_as_float(h.w & 0xffff0000u) + __uint_as_float(l.w & 0xffff0000u)}; }
;                     const f32x4 v0 = b0 + acc[ai][bj][mh + m][0] * scale + bv[bj][0], v1 = b1 + acc[ai][bj][mh + m][1] * scale + bv[bj][1];
;                     if (fout) { *(f32x4*)(fout + c) = v0; *(f32x4*)(fout + c + 4) = v1; }
;                     else { const unsigned h0 = pk2(v0[0], v0[1]), h1 = pk2(v0[2], v0[3]), h2 = pk2(v1[0], v1[1]), h3 = pk2(v1[2], v1[3]);
;                         const unsigned l0 = pk2(v0[0] - __uint_as_float(h0 << 16), v0[1] - __uint_as_float(h0 & 0xffff0000u)), l1 = pk2(v0[2] - __uint_as_float(h1 << 16), v0[3] - __uint_as_float(h1 & 0xffff0000u)),
.Lepi3_nobias:
	v_add_u32_e32 v217, 0x0, v212
	global_load_dwordx4 v[148:151], v217, s[78:79]
	global_load_dwordx4 v[156:159], v217, s[78:79] offset:64
	global_load_dwordx4 v[152:155], v217, s[26:27]
	global_load_dwordx4 v[160:163], v217, s[26:27] offset:64
	v_add_u32_e32 v217, 0x8000, v212
	global_load_dwordx4 v[164:167], v217, s[78:79]
	global_load_dwordx4 v[172:175], v217, s[78:79] offset:64
	global_load_dwordx4 v[168:171], v217, s[26:27]
	global_load_dwordx4 v[176:179], v217, s[26:27] offset:64
	v_add_u32_e32 v217, 0x10000, v212
	global_load_dwordx4 v[196:199], v217, s[78:79]
	global_load_dwordx4 v[204:207], v217, s[78:79] offset:64
	global_load_dwordx4 v[200:203], v217, s[26:27]
	global_load_dwordx4 v[208:211], v217, s[26:27] offset:64
	s_waitcnt vmcnt(8)
	v_lshlrev_b32_e32 v218, 16, v148
	v_and_b32_e32 v219, 0xffff0000, v148
	v_lshlrev_b32_e32 v220, 16, v152
	v_and_b32_e32 v221, 0xffff0000, v152
	v_pk_add_f32 v[218:219], v[220:221], v[218:219]
	s_nop 0
	v_pk_fma_f32 v[144:145], s[20:21], v[144:145], v[218:219]
	v_lshlrev_b32_e32 v222, 16, v149
	v_and_b32_e32 v223, 0xffff0000, v149
	v_lshlrev_b32_e32 v250, 16, v153
	v_and_b32_e32 v251, 0xffff0000, v153
	v_pk_add_f32 v[222:223], v[250:251], v[222:223]
	s_nop 0
	v_pk_fma_f32 v[146:147], s[20:21], v[146:147], v[222:223]
	v_lshlrev_b32_e32 v218, 16, v150
	v_and_b32_e32 v219, 0xffff0000, v150
	v_lshlrev_b32_e32 v220, 16, v154
	v_and_b32_e32 v221, 0xffff0000, v154
	v_pk_add_f32 v[218:219], v[220:221], v[218:219]
	s_nop 0
	v_pk_fma_f32 v[140:141], s[20:21], v[140:141], v[218:219]
	v_lshlrev_b32_e32 v222, 16, v151
	v_and_b32_e32 v223, 0xffff0000, v151
	v_lshlrev_b32_e32 v250, 16, v155
	v_and_b32_e32 v251, 0xffff0000, v155
	v_pk_add_f32 v[222:223], v[250:251], v[222:223]
	s_nop 0
	v_pk_fma_f32 v[142:143], s[20:21], v[142:143], v[222:223]
	v_pk_add_f32 v[144:145], v[56:57], v[144:145]
	v_pk_add_f32 v[146:147], v[58:59], v[146:147]
	v_pk_add_f32 v[140:141], v[48:49], v[140:141]
	v_pk_add_f32 v[142:143], v[50:51], v[142:143]
	v_mul_f32_e32 v247, v144, v144
	v_mul_f32_e32 v249, v146, v146
	v_fmac_f32_e32 v247, v145, v145
	v_fmac_f32_e32 v249, v147, v147
	v_mul_f32_e32 v252, v140, v140
	v_add_f32_e32 v247, v247, v249
	v_mul_f32_e32 v249, v142, v142
	v_fmac_f32_e32 v252, v141, v141
	v_fmac_f32_e32 v249, v143, v143
	v_add_f32_e32 v252, v252, v249
	v_add_f32_e32 v247, v247, v252
	v_mov_b32_e32 v213, v247
	v_cvt_pk_bf16_f32 v148, v144, v145
	v_lshlrev_b32_e32 v218, 16, v148
	v_and_b32_e32 v219, 0xffff0000, v148
	v_pk_add_f32 v[144:145], v[144:145], v[218:219] neg_lo:[0,1] neg_hi:[0,1]
	s_nop 0
	v_cvt_pk_bf16_f32 v152, v144, v145
	v_cvt_pk_bf16_f32 v149, v146, v147
	v_lshlrev_b32_e32 v222, 16, v149
	v_and_b32_e32 v223, 0xffff0000, v149
	v_pk_add_f32 v[146:147], v[146:147], v[222:223] neg_lo:[0,1] neg_hi:[0,1]
	s_nop 0
	v_cvt_pk_bf16_f32 v153, v146, v147
	v_cvt_pk_bf16_f32 v150, v140, v141
	v_lshlrev_b32_e32 v218, 16, v150
	v_and_b32_e32 v219, 0xffff0000, v150
	v_pk_add_f32 v[140:141], v[140:141], v[218:219] neg_lo:[0,1] neg_hi:[0,1]
	s_nop 0
	v_cvt_pk_bf16_f32 v154, v140, v141
	v_cvt_pk_bf16_f32 v151, v142, v143
	v_lshlrev_b32_e32 v222, 16, v151
	v_and_b32_e32 v223, 0xffff0000, v151
	v_pk_add_f32 v[142:143], v[142:143], v[222:223] neg_lo:[0,1] neg_hi:[0,1]
	s_nop 0
	v_cvt_pk_bf16_f32 v155, v142, v143
	v_lshlrev_b32_e32 v218, 16, v156
	v_and_b32_e32 v219, 0xffff0000, v156
	v_lshlrev_b32_e32 v220, 16, v160
	v_and_b32_e32 v221, 0xffff0000, v160
	v_pk_add_f32 v[218:219], v[220:221], v[218:219]
	s_nop 0
	v_pk_fma_f32 v[136:137], s[20:21], v[136:137], v[218:219]
	v_lshlrev_b32_e32 v222, 16, v157
	v_and_b32_e32 v223, 0xffff0000, v157
	v_lshlrev_b32_e32 v250, 16, v161
	v_and_b32_e32 v251, 0xffff0000, v161
	v_pk_add_f32 v[222:223], v[250:251], v[222:223]
	s_nop 0
	v_pk_fma_f32 v[138:139], s[20:21], v[138:139], v[222:223]
	v_lshlrev_b32_e32 v218, 16, v158
	v_and_b32_e32 v219, 0xffff0000, v158
	v_lshlrev_b32_e32 v220, 16, v162
	v_and_b32_e32 v221, 0xffff0000, v162
	v_pk_add_f32 v[218:219], v[220:221], v[218:219]
	s_nop 0
	v_pk_fma_f32 v[132:133], s[20:21], v[132:133], v[218:219]
	v_lshlrev_b32_e32 v222, 16, v159
	v_and_b32_e32 v223, 0xffff0000, v159
	v_lshlrev_b32_e32 v250, 16, v163
	v_and_b32_e32 v251, 0xffff0000, v163
	v_pk_add_f32 v[222:223], v[250:251], v[222:223]
	s_nop 0
	v_pk_fma_f32 v[134:135], s[20:21], v[134:135], v[222:223]
	v_pk_add_f32 v[136:137], v[40:41], v[136:137]
	v_pk_add_f32 v[138:139], v[42:43], v[138:139]
	v_pk_add_f32 v[132:133], v[36:37], v[132:133]
	v_pk_add_f32 v[134:135], v[38:39], v[134:135]
	v_mul_f32_e32 v247, v136, v136
	v_mul_f32_e32 v249, v138, v138
	v_fmac_f32_e32 v247, v137, v137
	v_fmac_f32_e32 v249, v139, v139
	v_mul_f32_e32 v252, v132, v132
	v_add_f32_e32 v247, v247, v249
	v_mul_f32_e32 v249, v134, v134
	v_fmac_f32_e32 v252, v133, v133
	v_fmac_f32_e32 v249, v135, v135
	v_add_f32_e32 v252, v252, v249
	v_add_f32_e32 v247, v247, v252
	v_add_f32_e32 v213, v213, v247
	v_cvt_pk_bf16_f32 v156, v136, v137
	v_lshlrev_b32_e32 v218, 16, v156
	v_and_b32_e32 v219, 0xffff0000, v156
	v_pk_add_f32 v[136:137], v[136:137], v[218:219] neg_lo:[0,1] neg_hi:[0,1]
	s_nop 0
	v_cvt_pk_bf16_f32 v160, v136, v137
	v_cvt_pk_bf16_f32 v157, v138, v139
	v_lshlrev_b32_e32 v222, 16, v157
	v_and_b32_e32 v223, 0xffff0000, v157
	v_pk_add_f32 v[138:139], v[138:139], v[222:223] neg_lo:[0,1] neg_hi:[0,1]
	s_nop 0
	v_cvt_pk_bf16_f32 v161, v138, v139
	v_cvt_pk_bf16_f32 v158, v132, v133
	v_lshlrev_b32_e32 v218, 16, v158
	v_and_b32_e32 v219, 0xffff0000, v158
	v_pk_add_f32 v[132:133], v[132:133], v[218:219] neg_lo:[0,1] neg_hi:[0,1]
	s_nop 0
	v_cvt_pk_bf16_f32 v162, v132, v133
	v_cvt_pk_bf16_f32 v159, v134, v135
	v_lshlrev_b32_e32 v222, 16, v159
	v_and_b32_e32 v223, 0xffff0000, v159
	v_pk_add_f32 v[134:135], v[134:135], v[222:223] neg_lo:[0,1] neg_hi:[0,1]
	s_nop 0
	v_cvt_pk_bf16_f32 v163, v134, v135
	v_add_u32_e32 v217, 0x18000, v212
	global_load_dwordx4 v[132:135], v217, s[78:79]
	global_load_dwordx4 v[140:143], v217, s[78:79] offset:64
	global_load_dwordx4 v[136:139], v217, s[26:27]
	global_load_dwordx4 v[144:147], v217, s[26:27] offset:64
	v_add_u32_e32 v245, 0x0, v212
	global_store_dwordx4 v245, v[148:151], s[78:79]
	global_store_dwordx4 v245, v[156:159], s[78:79] offset:64
	global_store_dwordx4 v245, v[152:155], s[28:29]
	global_store_dwordx4 v245, v[160:163], s[28:29] offset:64
	s_waitcnt vmcnt(12)
;     __device__ __forceinline__ void operator()(const f32x4 (&acc)[2][2][4][2], const Unit& u, int wr, int wc, int fr, int fq) const {
;     ...
;                 for (int bj = 0; bj < 2; ++bj) { const size_t c = (size_t)(row0 + ai * HALF + (mh + m) * 16) * 1024 + col0 + bj * 32;
;                     if (xin) { rh[m][bj] = __builtin_bit_cast(u32x4, *(const f32x4*)(xin + c)); rl[m][bj] = __builtin_bit_cast(u32x4, *(const f32x4*)(xin + c + 4)); }
;                     else { rh[m][bj] = *(const u32x4*)(hi + c); rl[m][bj] = *(const u32x4*)(lo_in + c); } }
; #pragma unroll
;             for (int m = 0; m < 2; ++m) { const int r = row0 + ai * HALF + (mh + m) * 16; float s = 0.f;
; #pragma unroll
;                 for (int bj = 0; bj < 2; ++bj) { const size_t c = (size_t)r * 1024 + col0 + bj * 32; const u32x4 h = rh[m][bj], l = rl[m][bj]; f32x4 b0, b1;
;                     if (xin) { b0 = __builtin_bit_cast(f32x4, h); b1 = __builtin_bit_cast(f32x4, l); }
;                     else { b0 = (f32x4){__uint_as_float(h.x << 16) + __uint_as_float(l.x << 16), __uint_as_float(h.x & 0xffff0000u) + __uint_as_float(l.x & 0xffff0000u),
;                                         __uint_as_float(h.y << 16) + __uint_as_float(l.y << 16), __uint_as_float(h.y & 0xffff0000u) + __uint_as_float(l.y & 0xffff0000u)};
;                            b1 = (f32x4){__uint_as_float(h.z << 16) + __uint_as_float(l.z << 16), __uint_as_float(h.z & 0xffff0000u) + __uint_as_float(l.z & 0xffff0000u),
;                                         __uint_as_float(h.w << 16) + __uint_as_float(l.w << 16), __uint_as_float(h.w & 0xffff0000u) + __uint_as_float(l.w & 0xffff0000u)}; }
;                     const f32x4 v0 = b0 + acc[ai][bj][mh + m][0] * scale + bv[bj][0], v1 = b1 + acc[ai][bj][mh + m][1] * scale + bv[bj][1];
;                     if (fout) { *(f32x4*)(fout + c) = v0; *(f32x4*)(fout + c + 4) = v1; }
;                     else { const unsigned h0 = pk2(v0[0], v0[1]), h1 = pk2(v0[2], v0[3]), h2 = pk2(v1[0], v1[1]), h3 = pk2(v1[2], v1[3]);
;                         const unsigned l0 = pk2(v0[0] - __uint_as_float(h0 << 16), v0[1] - __uint_as_float(h0 & 0xffff0000u)), l1 = pk2(v0[2] - __uint_as_float(h1 << 16), v0[3] - __uint_as_float(h1 & 0xffff0000u)),
	v_lshlrev_b32_e32 v218, 16, v164
	v_and_b32_e32 v219, 0xffff0000, v164
	v_lshlrev_b32_e32 v220, 16, v168
	v_and_b32_e32 v221, 0xffff0000, v168
	v_pk_add_f32 v[218:219], v[220:221], v[218:219]
	s_nop 0
	v_pk_fma_f32 v[128:129], s[20:21], v[128:129], v[218:219]
	v_lshlrev_b32_e32 v222, 16, v165
	v_and_b32_e32 v223, 0xffff0000, v165
	v_lshlrev_b32_e32 v250, 16, v169
	v_and_b32_e32 v251, 0xffff0000, v169
	v_pk_add_f32 v[222:223], v[250:251], v[222:223]
	s_nop 0
	v_pk_fma_f32 v[130:131], s[20:21], v[130:131], v[222:223]
	v_lshlrev_b32_e32 v218, 16, v166
	v_and_b32_e32 v219, 0xffff0000, v166
	v_lshlrev_b32_e32 v220, 16, v170
	v_and_b32_e32 v221, 0xffff0000, v170
	v_pk_add_f32 v[218:219], v[220:221], v[218:219]
	s_nop 0
	v_pk_fma_f32 v[124:125], s[20:21], v[124:125], v[218:219]
	v_lshlrev_b32_e32 v222, 16, v167
	v_and_b32_e32 v223, 0xffff0000, v167
	v_lshlrev_b32_e32 v250, 16, v171
	v_and_b32_e32 v251, 0xffff0000, v171
	v_pk_add_f32 v[222:223], v[250:251], v[222:223]
	s_nop 0
	v_pk_fma_f32 v[126:127], s[20:21], v[126:127], v[222:223]
	v_pk_add_f32 v[128:129], v[56:57], v[128:129]
	v_pk_add_f32 v[130:131], v[58:59], v[130:131]
	v_pk_add_f32 v[124:125], v[48:49], v[124:125]
	v_pk_add_f32 v[126:127], v[50:51], v[126:127]
	v_mul_f32_e32 v247, v128, v128
	v_mul_f32_e32 v249, v130, v130
	v_fmac_f32_e32 v247, v129, v129
	v_fmac_f32_e32 v249, v131, v131
	v_mul_f32_e32 v252, v124, v124
	v_add_f32_e32 v247, v247, v249
	v_mul_f32_e32 v249, v126, v126
	v_fmac_f32_e32 v252, v125, v125
	v_fmac_f32_e32 v249, v127, v127
	v_add_f32_e32 v252, v252, v249
	v_add_f32_e32 v247, v247, v252
	v_mov_b32_e32 v148, v247
	v_cvt_pk_bf16_f32 v164, v128, v129
	v_lshlrev_b32_e32 v218, 16, v164
	v_and_b32_e32 v219, 0xffff0000, v164
	v_pk_add_f32 v[128:129], v[128:129], v[218:219] neg_lo:[0,1] neg_hi:[0,1]
	s_nop 0
	v_cvt_pk_bf16_f32 v168, v128, v129
	v_cvt_pk_bf16_f32 v165, v130, v131
	v_lshlrev_b32_e32 v222, 16, v165
	v_and_b32_e32 v223, 0xffff0000, v165
	v_pk_add_f32 v[130:131], v[130:131], v[222:223] neg_lo:[0,1] neg_hi:[0,1]
	s_nop 0
	v_cvt_pk_bf16_f32 v169, v130, v131
	v_cvt_pk_bf16_f32 v166, v124, v125
	v_lshlrev_b32_e32 v218, 16, v166
	v_and_b32_e32 v219, 0xffff0000, v166
	v_pk_add_f32 v[124:125], v[124:125], v[218:219] neg_lo:[0,1] neg_hi:[0,1]
	s_nop 0
	v_cvt_pk_bf16_f32 v170, v124, v125
	v_cvt_pk_bf16_f32 v167, v126, v127
	v_lshlrev_b32_e32 v222, 16, v167
	v_and_b32_e32 v223, 0xffff0000, v167
	v_pk_add_f32 v[126:127], v[126:127], v[222:223] neg_lo:[0,1] neg_hi:[0,1]
	s_nop 0
	v_cvt_pk_bf16_f32 v171, v126, v127
	v_lshlrev_b32_e32 v218, 16, v172
	v_and_b32_e32 v219, 0xffff0000, v172
	v_lshlrev_b32_e32 v220, 16, v176
	v_and_b32_e32 v221, 0xffff0000, v176
	v_pk_add_f32 v[218:219], v[220:221], v[218:219]
	s_nop 0
	v_pk_fma_f32 v[120:121], s[20:21], v[120:121], v[218:219]
	v_lshlrev_b32_e32 v222, 16, v173
	v_and_b32_e32 v223, 0xffff0000, v173
	v_lshlrev_b32_e32 v250, 16, v177
	v_and_b32_e32 v251, 0xffff0000, v177
	v_pk_add_f32 v[222:223], v[250:251], v[222:223]
	s_nop 0
	v_pk_fma_f32 v[122:123], s[20:21], v[122:123], v[222:223]
	v_lshlrev_b32_e32 v218, 16, v174
	v_and_b32_e32 v219, 0xffff0000, v174
	v_lshlrev_b32_e32 v220, 16, v178
	v_and_b32_e32 v221, 0xffff0000, v178
	v_pk_add_f32 v[218:219], v[220:221], v[218:219]
	s_nop 0
	v_pk_fma_f32 v[116:117], s[20:21], v[116:117], v[218:219]
	v_lshlrev_b32_e32 v222, 16, v175
	v_and_b32_e32 v223, 0xffff0000, v175
	v_lshlrev_b32_e32 v250, 16, v179
	v_and_b32_e32 v251, 0xffff0000, v179
	v_pk_add_f32 v[222:223], v[250:251], v[222:223]
	s_nop 0
	v_pk_fma_f32 v[118:119], s[20:21], v[118:119], v[222:223]
	v_pk_add_f32 v[120:121], v[40:41], v[120:121]
	v_pk_add_f32 v[122:123], v[42:43], v[122:123]
	v_pk_add_f32 v[116:117], v[36:37], v[116:117]
	v_pk_add_f32 v[118:119], v[38:39], v[118:119]
	v_mul_f32_e32 v247, v120, v120
	v_mul_f32_e32 v249, v122, v122
	v_fmac_f32_e32 v247, v121, v121
	v_fmac_f32_e32 v249, v123, v123
	v_mul_f32_e32 v252, v116, v116
	v_add_f32_e32 v247, v247, v249
	v_mul_f32_e32 v249, v118, v118
	v_fmac_f32_e32 v252, v117, v117
	v_fmac_f32_e32 v249, v119, v119
	v_add_f32_e32 v252, v252, v249
	v_add_f32_e32 v247, v247, v252
	v_add_f32_e32 v148, v148, v247
	v_cvt_pk_bf16_f32 v172, v120, v121
	v_lshlrev_b32_e32 v218, 16, v172
	v_and_b32_e32 v219, 0xffff0000, v172
	v_pk_add_f32 v[120:121], v[120:121], v[218:219] neg_lo:[0,1] neg_hi:[0,1]
	s_nop 0
	v_cvt_pk_bf16_f32 v176, v120, v121
	v_cvt_pk_bf16_f32 v173, v122, v123
	v_lshlrev_b32_e32 v222, 16, v173
	v_and_b32_e32 v223, 0xffff0000, v173
	v_pk_add_f32 v[122:123], v[122:123], v[222:223] neg_lo:[0,1] neg_hi:[0,1]
	s_nop 0
	v_cvt_pk_bf16_f32 v177, v122, v123
	v_cvt_pk_bf16_f32 v174, v116, v117
	v_lshlrev_b32_e32 v218, 16, v174
	v_and_b32_e32 v219, 0xffff0000, v174
	v_pk_add_f32 v[116:117], v[116:117], v[218:219] neg_lo:[0,1] neg_hi:[0,1]
	s_nop 0
	v_cvt_pk_bf16_f32 v178, v116, v117
	v_cvt_pk_bf16_f32 v175, v118, v119
	v_lshlrev_b32_e32 v222, 16, v175
	v_and_b32_e32 v223, 0xffff0000, v175
	v_pk_add_f32 v[118:119], v[118:119], v[222:223] neg_lo:[0,1] neg_hi:[0,1]
	s_nop 0
	v_cvt_pk_bf16_f32 v179, v118, v119
	v_add_u32_e32 v217, 0x40000, v212
	global_load_dwordx4 v[116:119], v217, s[78:79]
	global_load_dwordx4 v[124:127], v217, s[78:79] offset:64
	global_load_dwordx4 v[120:123], v217, s[26:27]
	global_load_dwordx4 v[128:131], v217, s[26:27] offset:64
	v_add_u32_e32 v245, 0x8000, v212
	global_store_dwordx4 v245, v[164:167], s[78:79]
	global_store_dwordx4 v245, v[172:175], s[78:79] offset:64
	global_store_dwordx4 v245, v[168:171], s[28:29]
	global_store_dwordx4 v245, v[176:179], s[28:29] offset:64
	s_waitcnt vmcnt(16)
;     __device__ __forceinline__ void operator()(const f32x4 (&acc)[2][2][4][2], const Unit& u, int wr, int wc, int fr, int fq) const {
;     ...
;                 for (int bj = 0; bj < 2; ++bj) { const size_t c = (size_t)(row0 + ai * HALF + (mh + m) * 16) * 1024 + col0 + bj * 32;
;                     if (xin) { rh[m][bj] = __builtin_bit_cast(u32x4, *(const f32x4*)(xin + c)); rl[m][bj] = __builtin_bit_cast(u32x4, *(const f32x4*)(xin + c + 4)); }
;                     else { rh[m][bj] = *(const u32x4*)(hi + c); rl[m][bj] = *(const u32x4*)(lo_in + c); } }
; #pragma unroll
;             for (int m = 0; m < 2; ++m) { const int r = row0 + ai * HALF + (mh + m) * 16; float s = 0.f;
; #pragma unroll
;                 for (int bj = 0; bj < 2; ++bj) { const size_t c = (size_t)r * 1024 + col0 + bj * 32; const u32x4 h = rh[m][bj], l = rl[m][bj]; f32x4 b0, b1;
;                     if (xin) { b0 = __builtin_bit_cast(f32x4, h); b1 = __builtin_bit_cast(f32x4, l); }
;                     else { b0 = (f32x4){__uint_as_float(h.x << 16) + __uint_as_float(l.x << 16), __uint_as_float(h.x & 0xffff0000u) + __uint_as_float(l.x & 0xffff0000u),
;                                         __uint_as_float(h.y << 16) + __uint_as_float(l.y << 16), __uint_as_float(h.y & 0xffff0000u) + __uint_as_float(l.y & 0xffff0000u)};
;                            b1 = (f32x4){__uint_as_float(h.z << 16) + __uint_as_float(l.z << 16), __uint_as_float(h.z & 0xffff0000u) + __uint_as_float(l.z & 0xffff0000u),
;                                         __uint_as_float(h.w << 16) + __uint_as_float(l.w << 16), __uint_as_float(h.w & 0xffff0000u) + __uint_as_float(l.w & 0xffff0000u)}; }
;                     const f32x4 v0 = b0 + acc[ai][bj][mh + m][0] * scale + bv[bj][0], v1 = b1 + acc[ai][bj][mh + m][1] * scale + bv[bj][1];
;                     if (fout) { *(f32x4*)(fout + c) = v0; *(f32x4*)(fout + c + 4) = v1; }
;                     else { const unsigned h0 = pk2(v0[0], v0[1]), h1 = pk2(v0[2], v0[3]), h2 = pk2(v1[0], v1[1]), h3 = pk2(v1[2], v1[3]);
;                         const unsigned l0 = pk2(v0[0] - __uint_as_float(h0 << 16), v0[1] - __uint_as_float(h0 & 0xffff0000u)), l1 = pk2(v0[2] - __uint_as_float(h1 << 16), v0[3] - __uint_as_float(h1 & 0xffff0000u)),
	v_lshlrev_b32_e32 v218, 16, v196
	v_and_b32_e32 v219, 0xffff0000, v196
	v_lshlrev_b32_e32 v220, 16, v200
	v_and_b32_e32 v221, 0xffff0000, v200
	v_pk_add_f32 v[218:219], v[220:221], v[218:219]
	s_nop 0
	v_pk_fma_f32 v[112:113], s[20:21], v[112:113], v[218:219]
	v_lshlrev_b32_e32 v222, 16, v197
	v_and_b32_e32 v223, 0xffff0000, v197
	v_lshlrev_b32_e32 v250, 16, v201
	v_and_b32_e32 v251, 0xffff0000, v201
	v_pk_add_f32 v[222:223], v[250:251], v[222:223]
	s_nop 0
	v_pk_fma_f32 v[114:115], s[20:21], v[114:115], v[222:223]
	v_lshlrev_b32_e32 v218, 16, v198
	v_and_b32_e32 v219, 0xffff0000, v198
	v_lshlrev_b32_e32 v220, 16, v202
	v_and_b32_e32 v221, 0xffff0000, v202
	v_pk_add_f32 v[218:219], v[220:221], v[218:219]
	s_nop 0
	v_pk_fma_f32 v[108:109], s[20:21], v[108:109], v[218:219]
	v_lshlrev_b32_e32 v222, 16, v199
	v_and_b32_e32 v223, 0xffff0000, v199
	v_lshlrev_b32_e32 v250, 16, v203
	v_and_b32_e32 v251, 0xffff0000, v203
	v_pk_add_f32 v[222:223], v[250:251], v[222:223]
	s_nop 0
	v_pk_fma_f32 v[110:111], s[20:21], v[110:111], v[222:223]
	v_pk_add_f32 v[112:113], v[56:57], v[112:113]
	v_pk_add_f32 v[114:115], v[58:59], v[114:115]
	v_pk_add_f32 v[108:109], v[48:49], v[108:109]
	v_pk_add_f32 v[110:111], v[50:51], v[110:111]
	v_mul_f32_e32 v247, v112, v112
	v_mul_f32_e32 v249, v114, v114
	v_fmac_f32_e32 v247, v113, v113
	v_fmac_f32_e32 v249, v115, v115
	v_mul_f32_e32 v252, v108, v108
	v_add_f32_e32 v247, v247, v249
	v_mul_f32_e32 v249, v110, v110
	v_fmac_f32_e32 v252, v109, v109
	v_fmac_f32_e32 v249, v111, v111
	v_add_f32_e32 v252, v252, v249
	v_add_f32_e32 v247, v247, v252
	v_mov_b32_e32 v149, v247
	v_cvt_pk_bf16_f32 v196, v112, v113
	v_lshlrev_b32_e32 v218, 16, v196
	v_and_b32_e32 v219, 0xffff0000, v196
	v_pk_add_f32 v[112:113], v[112:113], v[218:219] neg_lo:[0,1] neg_hi:[0,1]
	s_nop 0
	v_cvt_pk_bf16_f32 v200, v112, v113
	v_cvt_pk_bf16_f32 v197, v114, v115
	v_lshlrev_b32_e32 v222, 16, v197
	v_and_b32_e32 v223, 0xffff0000, v197
	v_pk_add_f32 v[114:115], v[114:115], v[222:223] neg_lo:[0,1] neg_hi:[0,1]
	s_nop 0
	v_cvt_pk_bf16_f32 v201, v114, v115
	v_cvt_pk_bf16_f32 v198, v108, v109
	v_lshlrev_b32_e32 v218, 16, v198
	v_and_b32_e32 v219, 0xffff0000, v198
	v_pk_add_f32 v[108:109], v[108:109], v[218:219] neg_lo:[0,1] neg_hi:[0,1]
	s_nop 0
	v_cvt_pk_bf16_f32 v202, v108, v109
	v_cvt_pk_bf16_f32 v199, v110, v111
	v_lshlrev_b32_e32 v222, 16, v199
	v_and_b32_e32 v223, 0xffff0000, v199
	v_pk_add_f32 v[110:111], v[110:111], v[222:223] neg_lo:[0,1] neg_hi:[0,1]
	s_nop 0
	v_cvt_pk_bf16_f32 v203, v110, v111
	v_lshlrev_b32_e32 v218, 16, v204
	v_and_b32_e32 v219, 0xffff0000, v204
	v_lshlrev_b32_e32 v220, 16, v208
	v_and_b32_e32 v221, 0xffff0000, v208
	v_pk_add_f32 v[218:219], v[220:221], v[218:219]
	s_nop 0
	v_pk_fma_f32 v[104:105], s[20:21], v[104:105], v[218:219]
	v_lshlrev_b32_e32 v222, 16, v205
	v_and_b32_e32 v223, 0xffff0000, v205
	v_lshlrev_b32_e32 v250, 16, v209
	v_and_b32_e32 v251, 0xffff0000, v209
	v_pk_add_f32 v[222:223], v[250:251], v[222:223]
	s_nop 0
	v_pk_fma_f32 v[106:107], s[20:21], v[106:107], v[222:223]
	v_lshlrev_b32_e32 v218, 16, v206
	v_and_b32_e32 v219, 0xffff0000, v206
	v_lshlrev_b32_e32 v220, 16, v210
	v_and_b32_e32 v221, 0xffff0000, v210
	v_pk_add_f32 v[218:219], v[220:221], v[218:219]
	s_nop 0
	v_pk_fma_f32 v[100:101], s[20:21], v[100:101], v[218:219]
	v_lshlrev_b32_e32 v222, 16, v207
	v_and_b32_e32 v223, 0xffff0000, v207
	v_lshlrev_b32_e32 v250, 16, v211
	v_and_b32_e32 v251, 0xffff0000, v211
	v_pk_add_f32 v[222:223], v[250:251], v[222:223]
	s_nop 0
	v_pk_fma_f32 v[102:103], s[20:21], v[102:103], v[222:223]
	v_pk_add_f32 v[104:105], v[40:41], v[104:105]
	v_pk_add_f32 v[106:107], v[42:43], v[106:107]
	v_pk_add_f32 v[100:101], v[36:37], v[100:101]
	v_pk_add_f32 v[102:103], v[38:39], v[102:103]
	v_mul_f32_e32 v247, v104, v104
	v_mul_f32_e32 v249, v106, v106
	v_fmac_f32_e32 v247, v105, v105
	v_fmac_f32_e32 v249, v107, v107
	v_mul_f32_e32 v252, v100, v100
	v_add_f32_e32 v247, v247, v249
	v_mul_f32_e32 v249, v102, v102
	v_fmac_f32_e32 v252, v101, v101
	v_fmac_f32_e32 v249, v103, v103
	v_add_f32_e32 v252, v252, v249
	v_add_f32_e32 v247, v247, v252
	v_add_f32_e32 v149, v149, v247
	v_cvt_pk_bf16_f32 v204, v104, v105
	v_lshlrev_b32_e32 v218, 16, v204
	v_and_b32_e32 v219, 0xffff0000, v204
	v_pk_add_f32 v[104:105], v[104:105], v[218:219] neg_lo:[0,1] neg_hi:[0,1]
	s_nop 0
	v_cvt_pk_bf16_f32 v208, v104, v105
	v_cvt_pk_bf16_f32 v205, v106, v107
	v_lshlrev_b32_e32 v222, 16, v205
	v_and_b32_e32 v223, 0xffff0000, v205
	v_pk_add_f32 v[106:107], v[106:107], v[222:223] neg_lo:[0,1] neg_hi:[0,1]
	s_nop 0
	v_cvt_pk_bf16_f32 v209, v106, v107
	v_cvt_pk_bf16_f32 v206, v100, v101
	v_lshlrev_b32_e32 v218, 16, v206
	v_and_b32_e32 v219, 0xffff0000, v206
	v_pk_add_f32 v[100:101], v[100:101], v[218:219] neg_lo:[0,1] neg_hi:[0,1]
	s_nop 0
	v_cvt_pk_bf16_f32 v210, v100, v101
	v_cvt_pk_bf16_f32 v207, v102, v103
	v_lshlrev_b32_e32 v222, 16, v207
	v_and_b32_e32 v223, 0xffff0000, v207
	v_pk_add_f32 v[102:103], v[102:103], v[222:223] neg_lo:[0,1] neg_hi:[0,1]
	s_nop 0
	v_cvt_pk_bf16_f32 v211, v102, v103
	v_add_u32_e32 v217, 0x48000, v212
	global_load_dwordx4 v[100:103], v217, s[78:79]
	global_load_dwordx4 v[108:111], v217, s[78:79] offset:64
	global_load_dwordx4 v[104:107], v217, s[26:27]
	global_load_dwordx4 v[112:115], v217, s[26:27] offset:64
	v_add_u32_e32 v245, 0x10000, v212
	global_store_dwordx4 v245, v[196:199], s[78:79]
	global_store_dwordx4 v245, v[204:207], s[78:79] offset:64
	global_store_dwordx4 v245, v[200:203], s[28:29]
	global_store_dwordx4 v245, v[208:211], s[28:29] offset:64
	s_waitcnt vmcnt(20)
;     __device__ __forceinline__ void operator()(const f32x4 (&acc)[2][2][4][2], const Unit& u, int wr, int wc, int fr, int fq) const {
;     ...
;                 for (int bj = 0; bj < 2; ++bj) { const size_t c = (size_t)(row0 + ai * HALF + (mh + m) * 16) * 1024 + col0 + bj * 32;
;                     if (xin) { rh[m][bj] = __builtin_bit_cast(u32x4, *(const f32x4*)(xin + c)); rl[m][bj] = __builtin_bit_cast(u32x4, *(const f32x4*)(xin + c + 4)); }
;                     else { rh[m][bj] = *(const u32x4*)(hi + c); rl[m][bj] = *(const u32x4*)(lo_in + c); } }
; #pragma unroll
;             for (int m = 0; m < 2; ++m) { const int r = row0 + ai * HALF + (mh + m) * 16; float s = 0.f;
; #pragma unroll
;                 for (int bj = 0; bj < 2; ++bj) { const size_t c = (size_t)r * 1024 + col0 + bj * 32; const u32x4 h = rh[m][bj], l = rl[m][bj]; f32x4 b0, b1;
;                     if (xin) { b0 = __builtin_bit_cast(f32x4, h); b1 = __builtin_bit_cast(f32x4, l); }
;                     else { b0 = (f32x4){__uint_as_float(h.x << 16) + __uint_as_float(l.x << 16), __uint_as_float(h.x & 0xffff0000u) + __uint_as_float(l.x & 0xffff0000u),
;                                         __uint_as_float(h.y << 16) + __uint_as_float(l.y << 16), __uint_as_float(h.y & 0xffff0000u) + __uint_as_float(l.y & 0xffff0000u)};
;                            b1 = (f32x4){__uint_as_float(h.z << 16) + __uint_as_float(l.z << 16), __uint_as_float(h.z & 0xffff0000u) + __uint_as_float(l.z & 0xffff0000u),
;                                         __uint_as_float(h.w << 16) + __uint_as_float(l.w << 16), __uint_as_float(h.w & 0xffff0000u) + __uint_as_float(l.w & 0xffff0000u)}; }
;                     const f32x4 v0 = b0 + acc[ai][bj][mh + m][0] * scale + bv[bj][0], v1 = b1 + acc[ai][bj][mh + m][1] * scale + bv[bj][1];
;                     if (fout) { *(f32x4*)(fout + c) = v0; *(f32x4*)(fout + c + 4) = v1; }
;                     else { const unsigned h0 = pk2(v0[0], v0[1]), h1 = pk2(v0[2], v0[3]), h2 = pk2(v1[0], v1[1]), h3 = pk2(v1[2], v1[3]);
;                         const unsigned l0 = pk2(v0[0] - __uint_as_float(h0 << 16), v0[1] - __uint_as_float(h0 & 0xffff0000u)), l1 = pk2(v0[2] - __uint_as_float(h1 << 16), v0[3] - __uint_as_float(h1 & 0xffff0000u)),
	v_lshlrev_b32_e32 v218, 16, v132
	v_and_b32_e32 v219, 0xffff0000, v132
	v_lshlrev_b32_e32 v220, 16, v136
	v_and_b32_e32 v221, 0xffff0000, v136
	v_pk_add_f32 v[218:219], v[220:221], v[218:219]
	s_nop 0
	v_pk_fma_f32 v[96:97], s[20:21], v[96:97], v[218:219]
	v_lshlrev_b32_e32 v222, 16, v133
	v_and_b32_e32 v223, 0xffff0000, v133
	v_lshlrev_b32_e32 v250, 16, v137
	v_and_b32_e32 v251, 0xffff0000, v137
	v_pk_add_f32 v[222:223], v[250:251], v[222:223]
	s_nop 0
	v_pk_fma_f32 v[98:99], s[20:21], v[98:99], v[222:223]
	v_lshlrev_b32_e32 v218, 16, v134
	v_and_b32_e32 v219, 0xffff0000, v134
	v_lshlrev_b32_e32 v220, 16, v138
	v_and_b32_e32 v221, 0xffff0000, v138
	v_pk_add_f32 v[218:219], v[220:221], v[218:219]
	s_nop 0
	v_pk_fma_f32 v[92:93], s[20:21], v[92:93], v[218:219]
	v_lshlrev_b32_e32 v222, 16, v135
	v_and_b32_e32 v223, 0xffff0000, v135
	v_lshlrev_b32_e32 v250, 16, v139
	v_and_b32_e32 v251, 0xffff0000, v139
	v_pk_add_f32 v[222:223], v[250:251], v[222:223]
	s_nop 0
	v_pk_fma_f32 v[94:95], s[20:21], v[94:95], v[222:223]
	v_pk_add_f32 v[96:97], v[56:57], v[96:97]
	v_pk_add_f32 v[98:99], v[58:59], v[98:99]
	v_pk_add_f32 v[92:93], v[48:49], v[92:93]
	v_pk_add_f32 v[94:95], v[50:51], v[94:95]
	v_mul_f32_e32 v247, v96, v96
	v_mul_f32_e32 v249, v98, v98
	v_fmac_f32_e32 v247, v97, v97
	v_fmac_f32_e32 v249, v99, v99
	v_mul_f32_e32 v252, v92, v92
	v_add_f32_e32 v247, v247, v249
	v_mul_f32_e32 v249, v94, v94
	v_fmac_f32_e32 v252, v93, v93
	v_fmac_f32_e32 v249, v95, v95
	v_add_f32_e32 v252, v252, v249
	v_add_f32_e32 v247, v247, v252
	v_mov_b32_e32 v150, v247
	v_cvt_pk_bf16_f32 v132, v96, v97
	v_lshlrev_b32_e32 v218, 16, v132
	v_and_b32_e32 v219, 0xffff0000, v132
	v_pk_add_f32 v[96:97], v[96:97], v[218:219] neg_lo:[0,1] neg_hi:[0,1]
	s_nop 0
	v_cvt_pk_bf16_f32 v136, v96, v97
	v_cvt_pk_bf16_f32 v133, v98, v99
	v_lshlrev_b32_e32 v222, 16, v133
	v_and_b32_e32 v223, 0xffff0000, v133
	v_pk_add_f32 v[98:99], v[98:99], v[222:223] neg_lo:[0,1] neg_hi:[0,1]
	s_nop 0
	v_cvt_pk_bf16_f32 v137, v98, v99
	v_cvt_pk_bf16_f32 v134, v92, v93
	v_lshlrev_b32_e32 v218, 16, v134
	v_and_b32_e32 v219, 0xffff0000, v134
	v_pk_add_f32 v[92:93], v[92:93], v[218:219] neg_lo:[0,1] neg_hi:[0,1]
	s_nop 0
	v_cvt_pk_bf16_f32 v138, v92, v93
	v_cvt_pk_bf16_f32 v135, v94, v95
	v_lshlrev_b32_e32 v222, 16, v135
	v_and_b32_e32 v223, 0xffff0000, v135
	v_pk_add_f32 v[94:95], v[94:95], v[222:223] neg_lo:[0,1] neg_hi:[0,1]
	s_nop 0
	v_cvt_pk_bf16_f32 v139, v94, v95
	v_lshlrev_b32_e32 v218, 16, v140
	v_and_b32_e32 v219, 0xffff0000, v140
	v_lshlrev_b32_e32 v220, 16, v144
	v_and_b32_e32 v221, 0xffff0000, v144
	v_pk_add_f32 v[218:219], v[220:221], v[218:219]
	s_nop 0
	v_pk_fma_f32 v[88:89], s[20:21], v[88:89], v[218:219]
	v_lshlrev_b32_e32 v222, 16, v141
	v_and_b32_e32 v223, 0xffff0000, v141
	v_lshlrev_b32_e32 v250, 16, v145
	v_and_b32_e32 v251, 0xffff0000, v145
	v_pk_add_f32 v[222:223], v[250:251], v[222:223]
	s_nop 0
	v_pk_fma_f32 v[90:91], s[20:21], v[90:91], v[222:223]
	v_lshlrev_b32_e32 v218, 16, v142
	v_and_b32_e32 v219, 0xffff0000, v142
	v_lshlrev_b32_e32 v220, 16, v146
	v_and_b32_e32 v221, 0xffff0000, v146
	v_pk_add_f32 v[218:219], v[220:221], v[218:219]
	s_nop 0
	v_pk_fma_f32 v[84:85], s[20:21], v[84:85], v[218:219]
	v_lshlrev_b32_e32 v222, 16, v143
	v_and_b32_e32 v223, 0xffff0000, v143
	v_lshlrev_b32_e32 v250, 16, v147
	v_and_b32_e32 v251, 0xffff0000, v147
	v_pk_add_f32 v[222:223], v[250:251], v[222:223]
	s_nop 0
	v_pk_fma_f32 v[86:87], s[20:21], v[86:87], v[222:223]
	v_pk_add_f32 v[88:89], v[40:41], v[88:89]
	v_pk_add_f32 v[90:91], v[42:43], v[90:91]
	v_pk_add_f32 v[84:85], v[36:37], v[84:85]
	v_pk_add_f32 v[86:87], v[38:39], v[86:87]
	v_mul_f32_e32 v247, v88, v88
	v_mul_f32_e32 v249, v90, v90
	v_fmac_f32_e32 v247, v89, v89
	v_fmac_f32_e32 v249, v91, v91
	v_mul_f32_e32 v252, v84, v84
	v_add_f32_e32 v247, v247, v249
	v_mul_f32_e32 v249, v86, v86
	v_fmac_f32_e32 v252, v85, v85
	v_fmac_f32_e32 v249, v87, v87
	v_add_f32_e32 v252, v252, v249
	v_add_f32_e32 v247, v247, v252
	v_add_f32_e32 v150, v150, v247
	v_cvt_pk_bf16_f32 v140, v88, v89
	v_lshlrev_b32_e32 v218, 16, v140
	v_and_b32_e32 v219, 0xffff0000, v140
	v_pk_add_f32 v[88:89], v[88:89], v[218:219] neg_lo:[0,1] neg_hi:[0,1]
	s_nop 0
	v_cvt_pk_bf16_f32 v144, v88, v89
	v_cvt_pk_bf16_f32 v141, v90, v91
	v_lshlrev_b32_e32 v222, 16, v141
	v_and_b32_e32 v223, 0xffff0000, v141
	v_pk_add_f32 v[90:91], v[90:91], v[222:223] neg_lo:[0,1] neg_hi:[0,1]
	s_nop 0
	v_cvt_pk_bf16_f32 v145, v90, v91
	v_cvt_pk_bf16_f32 v142, v84, v85
	v_lshlrev_b32_e32 v218, 16, v142
	v_and_b32_e32 v219, 0xffff0000, v142
	v_pk_add_f32 v[84:85], v[84:85], v[218:219] neg_lo:[0,1] neg_hi:[0,1]
	s_nop 0
	v_cvt_pk_bf16_f32 v146, v84, v85
	v_cvt_pk_bf16_f32 v143, v86, v87
	v_lshlrev_b32_e32 v222, 16, v143
	v_and_b32_e32 v223, 0xffff0000, v143
	v_pk_add_f32 v[86:87], v[86:87], v[222:223] neg_lo:[0,1] neg_hi:[0,1]
	s_nop 0
	v_cvt_pk_bf16_f32 v147, v86, v87
	v_add_u32_e32 v217, 0x50000, v212
	global_load_dwordx4 v[84:87], v217, s[78:79]
	global_load_dwordx4 v[92:95], v217, s[78:79] offset:64
	global_load_dwordx4 v[88:91], v217, s[26:27]
	global_load_dwordx4 v[96:99], v217, s[26:27] offset:64
	v_add_u32_e32 v245, 0x18000, v212
	global_store_dwordx4 v245, v[132:135], s[78:79]
	global_store_dwordx4 v245, v[140:143], s[78:79] offset:64
	global_store_dwordx4 v245, v[136:139], s[28:29]
	global_store_dwordx4 v245, v[144:147], s[28:29] offset:64
	s_waitcnt vmcnt(20)
;     __device__ __forceinline__ void operator()(const f32x4 (&acc)[2][2][4][2], const Unit& u, int wr, int wc, int fr, int fq) const {
;     ...
;                 for (int bj = 0; bj < 2; ++bj) { const size_t c = (size_t)(row0 + ai * HALF + (mh + m) * 16) * 1024 + col0 + bj * 32;
;                     if (xin) { rh[m][bj] = __builtin_bit_cast(u32x4, *(const f32x4*)(xin + c)); rl[m][bj] = __builtin_bit_cast(u32x4, *(const f32x4*)(xin + c + 4)); }
;                     else { rh[m][bj] = *(const u32x4*)(hi + c); rl[m][bj] = *(const u32x4*)(lo_in + c); } }
; #pragma unroll
;             for (int m = 0; m < 2; ++m) { const int r = row0 + ai * HALF + (mh + m) * 16; float s = 0.f;
; #pragma unroll
;                 for (int bj = 0; bj < 2; ++bj) { const size_t c = (size_t)r * 1024 + col0 + bj * 32; const u32x4 h = rh[m][bj], l = rl[m][bj]; f32x4 b0, b1;
;                     if (xin) { b0 = __builtin_bit_cast(f32x4, h); b1 = __builtin_bit_cast(f32x4, l); }
;                     else { b0 = (f32x4){__uint_as_float(h.x << 16) + __uint_as_float(l.x << 16), __uint_as_float(h.x & 0xffff0000u) + __uint_as_float(l.x & 0xffff0000u),
;                                         __uint_as_float(h.y << 16) + __uint_as_float(l.y << 16), __uint_as_float(h.y & 0xffff0000u) + __uint_as_float(l.y & 0xffff0000u)};
;                            b1 = (f32x4){__uint_as_float(h.z << 16) + __uint_as_float(l.z << 16), __uint_as_float(h.z & 0xffff0000u) + __uint_as_float(l.z & 0xffff0000u),
;                                         __uint_as_float(h.w << 16) + __uint_as_float(l.w << 16), __uint_as_float(h.w & 0xffff0000u) + __uint_as_float(l.w & 0xffff0000u)}; }
;                     const f32x4 v0 = b0 + acc[ai][bj][mh + m][0] * scale + bv[bj][0], v1 = b1 + acc[ai][bj][mh + m][1] * scale + bv[bj][1];
;                     if (fout) { *(f32x4*)(fout + c) = v0; *(f32x4*)(fout + c + 4) = v1; }
;                     else { const unsigned h0 = pk2(v0[0], v0[1]), h1 = pk2(v0[2], v0[3]), h2 = pk2(v1[0], v1[1]), h3 = pk2(v1[2], v1[3]);
;                         const unsigned l0 = pk2(v0[0] - __uint_as_float(h0 << 16), v0[1] - __uint_as_float(h0 & 0xffff0000u)), l1 = pk2(v0[2] - __uint_as_float(h1 << 16), v0[3] - __uint_as_float(h1 & 0xffff0000u)),
	v_lshlrev_b32_e32 v218, 16, v116
	v_and_b32_e32 v219, 0xffff0000, v116
	v_lshlrev_b32_e32 v220, 16, v120
	v_and_b32_e32 v221, 0xffff0000, v120
	v_pk_add_f32 v[218:219], v[220:221], v[218:219]
	s_nop 0
	v_pk_fma_f32 v[80:81], s[20:21], v[80:81], v[218:219]
	v_lshlrev_b32_e32 v222, 16, v117
	v_and_b32_e32 v223, 0xffff0000, v117
	v_lshlrev_b32_e32 v250, 16, v121
	v_and_b32_e32 v251, 0xffff0000, v121
	v_pk_add_f32 v[222:223], v[250:251], v[222:223]
	s_nop 0
	v_pk_fma_f32 v[82:83], s[20:21], v[82:83], v[222:223]
	v_lshlrev_b32_e32 v218, 16, v118
	v_and_b32_e32 v219, 0xffff0000, v118
	v_lshlrev_b32_e32 v220, 16, v122
	v_and_b32_e32 v221, 0xffff0000, v122
	v_pk_add_f32 v[218:219], v[220:221], v[218:219]
	s_nop 0
	v_pk_fma_f32 v[76:77], s[20:21], v[76:77], v[218:219]
	v_lshlrev_b32_e32 v222, 16, v119
	v_and_b32_e32 v223, 0xffff0000, v119
	v_lshlrev_b32_e32 v250, 16, v123
	v_and_b32_e32 v251, 0xffff0000, v123
	v_pk_add_f32 v[222:223], v[250:251], v[222:223]
	s_nop 0
	v_pk_fma_f32 v[78:79], s[20:21], v[78:79], v[222:223]
	v_pk_add_f32 v[80:81], v[56:57], v[80:81]
	v_pk_add_f32 v[82:83], v[58:59], v[82:83]
	v_pk_add_f32 v[76:77], v[48:49], v[76:77]
	v_pk_add_f32 v[78:79], v[50:51], v[78:79]
	v_mul_f32_e32 v247, v80, v80
	v_mul_f32_e32 v249, v82, v82
	v_fmac_f32_e32 v247, v81, v81
	v_fmac_f32_e32 v249, v83, v83
	v_mul_f32_e32 v252, v76, v76
	v_add_f32_e32 v247, v247, v249
	v_mul_f32_e32 v249, v78, v78
	v_fmac_f32_e32 v252, v77, v77
	v_fmac_f32_e32 v249, v79, v79
	v_add_f32_e32 v252, v252, v249
	v_add_f32_e32 v247, v247, v252
	v_mov_b32_e32 v151, v247
	v_cvt_pk_bf16_f32 v116, v80, v81
	v_lshlrev_b32_e32 v218, 16, v116
	v_and_b32_e32 v219, 0xffff0000, v116
	v_pk_add_f32 v[80:81], v[80:81], v[218:219] neg_lo:[0,1] neg_hi:[0,1]
	s_nop 0
	v_cvt_pk_bf16_f32 v120, v80, v81
	v_cvt_pk_bf16_f32 v117, v82, v83
	v_lshlrev_b32_e32 v222, 16, v117
	v_and_b32_e32 v223, 0xffff0000, v117
	v_pk_add_f32 v[82:83], v[82:83], v[222:223] neg_lo:[0,1] neg_hi:[0,1]
	s_nop 0
	v_cvt_pk_bf16_f32 v121, v82, v83
	v_cvt_pk_bf16_f32 v118, v76, v77
	v_lshlrev_b32_e32 v218, 16, v118
	v_and_b32_e32 v219, 0xffff0000, v118
	v_pk_add_f32 v[76:77], v[76:77], v[218:219] neg_lo:[0,1] neg_hi:[0,1]
	s_nop 0
	v_cvt_pk_bf16_f32 v122, v76, v77
	v_cvt_pk_bf16_f32 v119, v78, v79
	v_lshlrev_b32_e32 v222, 16, v119
	v_and_b32_e32 v223, 0xffff0000, v119
	v_pk_add_f32 v[78:79], v[78:79], v[222:223] neg_lo:[0,1] neg_hi:[0,1]
	s_nop 0
	v_cvt_pk_bf16_f32 v123, v78, v79
	v_lshlrev_b32_e32 v218, 16, v124
	v_and_b32_e32 v219, 0xffff0000, v124
	v_lshlrev_b32_e32 v220, 16, v128
	v_and_b32_e32 v221, 0xffff0000, v128
	v_pk_add_f32 v[218:219], v[220:221], v[218:219]
	s_nop 0
	v_pk_fma_f32 v[72:73], s[20:21], v[72:73], v[218:219]
	v_lshlrev_b32_e32 v222, 16, v125
	v_and_b32_e32 v223, 0xffff0000, v125
	v_lshlrev_b32_e32 v250, 16, v129
	v_and_b32_e32 v251, 0xffff0000, v129
	v_pk_add_f32 v[222:223], v[250:251], v[222:223]
	s_nop 0
	v_pk_fma_f32 v[74:75], s[20:21], v[74:75], v[222:223]
	v_lshlrev_b32_e32 v218, 16, v126
	v_and_b32_e32 v219, 0xffff0000, v126
	v_lshlrev_b32_e32 v220, 16, v130
	v_and_b32_e32 v221, 0xffff0000, v130
	v_pk_add_f32 v[218:219], v[220:221], v[218:219]
	s_nop 0
	v_pk_fma_f32 v[68:69], s[20:21], v[68:69], v[218:219]
	v_lshlrev_b32_e32 v222, 16, v127
	v_and_b32_e32 v223, 0xffff0000, v127
	v_lshlrev_b32_e32 v250, 16, v131
	v_and_b32_e32 v251, 0xffff0000, v131
	v_pk_add_f32 v[222:223], v[250:251], v[222:223]
	s_nop 0
	v_pk_fma_f32 v[70:71], s[20:21], v[70:71], v[222:223]
	v_pk_add_f32 v[72:73], v[40:41], v[72:73]
	v_pk_add_f32 v[74:75], v[42:43], v[74:75]
	v_pk_add_f32 v[68:69], v[36:37], v[68:69]
	v_pk_add_f32 v[70:71], v[38:39], v[70:71]
	v_mul_f32_e32 v247, v72, v72
	v_mul_f32_e32 v249, v74, v74
	v_fmac_f32_e32 v247, v73, v73
	v_fmac_f32_e32 v249, v75, v75
	v_mul_f32_e32 v252, v68, v68
	v_add_f32_e32 v247, v247, v249
	v_mul_f32_e32 v249, v70, v70
	v_fmac_f32_e32 v252, v69, v69
	v_fmac_f32_e32 v249, v71, v71
	v_add_f32_e32 v252, v252, v249
	v_add_f32_e32 v247, v247, v252
	v_add_f32_e32 v151, v151, v247
	v_cvt_pk_bf16_f32 v124, v72, v73
	v_lshlrev_b32_e32 v218, 16, v124
	v_and_b32_e32 v219, 0xffff0000, v124
	v_pk_add_f32 v[72:73], v[72:73], v[218:219] neg_lo:[0,1] neg_hi:[0,1]
	s_nop 0
	v_cvt_pk_bf16_f32 v128, v72, v73
	v_cvt_pk_bf16_f32 v125, v74, v75
	v_lshlrev_b32_e32 v222, 16, v125
	v_and_b32_e32 v223, 0xffff0000, v125
	v_pk_add_f32 v[74:75], v[74:75], v[222:223] neg_lo:[0,1] neg_hi:[0,1]
	s_nop 0
	v_cvt_pk_bf16_f32 v129, v74, v75
	v_cvt_pk_bf16_f32 v126, v68, v69
	v_lshlrev_b32_e32 v218, 16, v126
	v_and_b32_e32 v219, 0xffff0000, v126
	v_pk_add_f32 v[68:69], v[68:69], v[218:219] neg_lo:[0,1] neg_hi:[0,1]
	s_nop 0
	v_cvt_pk_bf16_f32 v130, v68, v69
	v_cvt_pk_bf16_f32 v127, v70, v71
	v_lshlrev_b32_e32 v222, 16, v127
	v_and_b32_e32 v223, 0xffff0000, v127
	v_pk_add_f32 v[70:71], v[70:71], v[222:223] neg_lo:[0,1] neg_hi:[0,1]
	s_nop 0
	v_cvt_pk_bf16_f32 v131, v70, v71
	v_add_u32_e32 v217, 0x58000, v212
	global_load_dwordx4 v[68:71], v217, s[78:79]
	global_load_dwordx4 v[76:79], v217, s[78:79] offset:64
	global_load_dwordx4 v[72:75], v217, s[26:27]
	global_load_dwordx4 v[80:83], v217, s[26:27] offset:64
	v_add_u32_e32 v245, 0x40000, v212
	global_store_dwordx4 v245, v[116:119], s[78:79]
	global_store_dwordx4 v245, v[124:127], s[78:79] offset:64
	global_store_dwordx4 v245, v[120:123], s[28:29]
	global_store_dwordx4 v245, v[128:131], s[28:29] offset:64
	s_waitcnt vmcnt(20)
;     __device__ __forceinline__ void operator()(const f32x4 (&acc)[2][2][4][2], const Unit& u, int wr, int wc, int fr, int fq) const {
;     ...
;                 for (int bj = 0; bj < 2; ++bj) { const size_t c = (size_t)(row0 + ai * HALF + (mh + m) * 16) * 1024 + col0 + bj * 32;
;                     if (xin) { rh[m][bj] = __builtin_bit_cast(u32x4, *(const f32x4*)(xin + c)); rl[m][bj] = __builtin_bit_cast(u32x4, *(const f32x4*)(xin + c + 4)); }
;                     else { rh[m][bj] = *(const u32x4*)(hi + c); rl[m][bj] = *(const u32x4*)(lo_in + c); } }
; #pragma unroll
;             for (int m = 0; m < 2; ++m) { const int r = row0 + ai * HALF + (mh + m) * 16; float s = 0.f;
; #pragma unroll
;                 for (int bj = 0; bj < 2; ++bj) { const size_t c = (size_t)r * 1024 + col0 + bj * 32; const u32x4 h = rh[m][bj], l = rl[m][bj]; f32x4 b0, b1;
;                     if (xin) { b0 = __builtin_bit_cast(f32x4, h); b1 = __builtin_bit_cast(f32x4, l); }
;                     else { b0 = (f32x4){__uint_as_float(h.x << 16) + __uint_as_float(l.x << 16), __uint_as_float(h.x & 0xffff0000u) + __uint_as_float(l.x & 0xffff0000u),
;                                         __uint_as_float(h.y << 16) + __uint_as_float(l.y << 16), __uint_as_float(h.y & 0xffff0000u) + __uint_as_float(l.y & 0xffff0000u)};
;                            b1 = (f32x4){__uint_as_float(h.z << 16) + __uint_as_float(l.z << 16), __uint_as_float(h.z & 0xffff0000u) + __uint_as_float(l.z & 0xffff0000u),
;                                         __uint_as_float(h.w << 16) + __uint_as_float(l.w << 16), __uint_as_float(h.w & 0xffff0000u) + __uint_as_float(l.w & 0xffff0000u)}; }
;                     const f32x4 v0 = b0 + acc[ai][bj][mh + m][0] * scale + bv[bj][0], v1 = b1 + acc[ai][bj][mh + m][1] * scale + bv[bj][1];
;                     if (fout) { *(f32x4*)(fout + c) = v0; *(f32x4*)(fout + c + 4) = v1; }
;                     else { const unsigned h0 = pk2(v0[0], v0[1]), h1 = pk2(v0[2], v0[3]), h2 = pk2(v1[0], v1[1]), h3 = pk2(v1[2], v1[3]);
;                         const unsigned l0 = pk2(v0[0] - __uint_as_float(h0 << 16), v0[1] - __uint_as_float(h0 & 0xffff0000u)), l1 = pk2(v0[2] - __uint_as_float(h1 << 16), v0[3] - __uint_as_float(h1 & 0xffff0000u)),
	v_lshlrev_b32_e32 v218, 16, v100
	v_and_b32_e32 v219, 0xffff0000, v100
	v_lshlrev_b32_e32 v220, 16, v104
	v_and_b32_e32 v221, 0xffff0000, v104
	v_pk_add_f32 v[218:219], v[220:221], v[218:219]
	s_nop 0
	v_pk_fma_f32 v[64:65], s[20:21], v[64:65], v[218:219]
	v_lshlrev_b32_e32 v222, 16, v101
	v_and_b32_e32 v223, 0xffff0000, v101
	v_lshlrev_b32_e32 v250, 16, v105
	v_and_b32_e32 v251, 0xffff0000, v105
	v_pk_add_f32 v[222:223], v[250:251], v[222:223]
	s_nop 0
	v_pk_fma_f32 v[66:67], s[20:21], v[66:67], v[222:223]
	v_lshlrev_b32_e32 v218, 16, v102
	v_and_b32_e32 v219, 0xffff0000, v102
	v_lshlrev_b32_e32 v220, 16, v106
	v_and_b32_e32 v221, 0xffff0000, v106
	v_pk_add_f32 v[218:219], v[220:221], v[218:219]
	s_nop 0
	v_pk_fma_f32 v[60:61], s[20:21], v[60:61], v[218:219]
	v_lshlrev_b32_e32 v222, 16, v103
	v_and_b32_e32 v223, 0xffff0000, v103
	v_lshlrev_b32_e32 v250, 16, v107
	v_and_b32_e32 v251, 0xffff0000, v107
	v_pk_add_f32 v[222:223], v[250:251], v[222:223]
	s_nop 0
	v_pk_fma_f32 v[62:63], s[20:21], v[62:63], v[222:223]
	v_pk_add_f32 v[64:65], v[56:57], v[64:65]
	v_pk_add_f32 v[66:67], v[58:59], v[66:67]
	v_pk_add_f32 v[60:61], v[48:49], v[60:61]
	v_pk_add_f32 v[62:63], v[50:51], v[62:63]
	v_mul_f32_e32 v247, v64, v64
	v_mul_f32_e32 v249, v66, v66
	v_fmac_f32_e32 v247, v65, v65
	v_fmac_f32_e32 v249, v67, v67
	v_mul_f32_e32 v252, v60, v60
	v_add_f32_e32 v247, v247, v249
	v_mul_f32_e32 v249, v62, v62
	v_fmac_f32_e32 v252, v61, v61
	v_fmac_f32_e32 v249, v63, v63
	v_add_f32_e32 v252, v252, v249
	v_add_f32_e32 v247, v247, v252
	v_mov_b32_e32 v152, v247
	v_cvt_pk_bf16_f32 v100, v64, v65
	v_lshlrev_b32_e32 v218, 16, v100
	v_and_b32_e32 v219, 0xffff0000, v100
	v_pk_add_f32 v[64:65], v[64:65], v[218:219] neg_lo:[0,1] neg_hi:[0,1]
	s_nop 0
	v_cvt_pk_bf16_f32 v104, v64, v65
	v_cvt_pk_bf16_f32 v101, v66, v67
	v_lshlrev_b32_e32 v222, 16, v101
	v_and_b32_e32 v223, 0xffff0000, v101
	v_pk_add_f32 v[66:67], v[66:67], v[222:223] neg_lo:[0,1] neg_hi:[0,1]
	s_nop 0
	v_cvt_pk_bf16_f32 v105, v66, v67
	v_cvt_pk_bf16_f32 v102, v60, v61
	v_lshlrev_b32_e32 v218, 16, v102
	v_and_b32_e32 v219, 0xffff0000, v102
	v_pk_add_f32 v[60:61], v[60:61], v[218:219] neg_lo:[0,1] neg_hi:[0,1]
	s_nop 0
	v_cvt_pk_bf16_f32 v106, v60, v61
	v_cvt_pk_bf16_f32 v103, v62, v63
	v_lshlrev_b32_e32 v222, 16, v103
	v_and_b32_e32 v223, 0xffff0000, v103
	v_pk_add_f32 v[62:63], v[62:63], v[222:223] neg_lo:[0,1] neg_hi:[0,1]
	s_nop 0
	v_cvt_pk_bf16_f32 v107, v62, v63
	v_lshlrev_b32_e32 v218, 16, v108
	v_and_b32_e32 v219, 0xffff0000, v108
	v_lshlrev_b32_e32 v220, 16, v112
	v_and_b32_e32 v221, 0xffff0000, v112
	v_pk_add_f32 v[218:219], v[220:221], v[218:219]
	s_nop 0
	v_pk_fma_f32 v[52:53], s[20:21], v[52:53], v[218:219]
	v_lshlrev_b32_e32 v222, 16, v109
	v_and_b32_e32 v223, 0xffff0000, v109
	v_lshlrev_b32_e32 v250, 16, v113
	v_and_b32_e32 v251, 0xffff0000, v113
	v_pk_add_f32 v[222:223], v[250:251], v[222:223]
	s_nop 0
	v_pk_fma_f32 v[54:55], s[20:21], v[54:55], v[222:223]
	v_lshlrev_b32_e32 v218, 16, v110
	v_and_b32_e32 v219, 0xffff0000, v110
	v_lshlrev_b32_e32 v220, 16, v114
	v_and_b32_e32 v221, 0xffff0000, v114
	v_pk_add_f32 v[218:219], v[220:221], v[218:219]
	s_nop 0
	v_pk_fma_f32 v[44:45], s[20:21], v[44:45], v[218:219]
	v_lshlrev_b32_e32 v222, 16, v111
	v_and_b32_e32 v223, 0xffff0000, v111
	v_lshlrev_b32_e32 v250, 16, v115
	v_and_b32_e32 v251, 0xffff0000, v115
	v_pk_add_f32 v[222:223], v[250:251], v[222:223]
	s_nop 0
	v_pk_fma_f32 v[46:47], s[20:21], v[46:47], v[222:223]
	v_pk_add_f32 v[52:53], v[40:41], v[52:53]
	v_pk_add_f32 v[54:55], v[42:43], v[54:55]
	v_pk_add_f32 v[44:45], v[36:37], v[44:45]
	v_pk_add_f32 v[46:47], v[38:39], v[46:47]
	v_mul_f32_e32 v247, v52, v52
	v_mul_f32_e32 v249, v54, v54
	v_fmac_f32_e32 v247, v53, v53
	v_fmac_f32_e32 v249, v55, v55
	v_mul_f32_e32 v252, v44, v44
	v_add_f32_e32 v247, v247, v249
	v_mul_f32_e32 v249, v46, v46
	v_fmac_f32_e32 v252, v45, v45
	v_fmac_f32_e32 v249, v47, v47
	v_add_f32_e32 v252, v252, v249
	v_add_f32_e32 v247, v247, v252
	v_add_f32_e32 v152, v152, v247
	v_cvt_pk_bf16_f32 v108, v52, v53
	v_lshlrev_b32_e32 v218, 16, v108
	v_and_b32_e32 v219, 0xffff0000, v108
	v_pk_add_f32 v[52:53], v[52:53], v[218:219] neg_lo:[0,1] neg_hi:[0,1]
	s_nop 0
	v_cvt_pk_bf16_f32 v112, v52, v53
	v_cvt_pk_bf16_f32 v109, v54, v55
	v_lshlrev_b32_e32 v222, 16, v109
	v_and_b32_e32 v223, 0xffff0000, v109
	v_pk_add_f32 v[54:55], v[54:55], v[222:223] neg_lo:[0,1] neg_hi:[0,1]
	s_nop 0
	v_cvt_pk_bf16_f32 v113, v54, v55
	v_cvt_pk_bf16_f32 v110, v44, v45
	v_lshlrev_b32_e32 v218, 16, v110
	v_and_b32_e32 v219, 0xffff0000, v110
	v_pk_add_f32 v[44:45], v[44:45], v[218:219] neg_lo:[0,1] neg_hi:[0,1]
	s_nop 0
	v_cvt_pk_bf16_f32 v114, v44, v45
	v_cvt_pk_bf16_f32 v111, v46, v47
	v_lshlrev_b32_e32 v222, 16, v111
	v_and_b32_e32 v223, 0xffff0000, v111
	v_pk_add_f32 v[46:47], v[46:47], v[222:223] neg_lo:[0,1] neg_hi:[0,1]
	s_nop 0
	v_cvt_pk_bf16_f32 v115, v46, v47
	v_add_u32_e32 v245, 0x48000, v212
	global_store_dwordx4 v245, v[100:103], s[78:79]
	global_store_dwordx4 v245, v[108:111], s[78:79] offset:64
	global_store_dwordx4 v245, v[104:107], s[28:29]
	global_store_dwordx4 v245, v[112:115], s[28:29] offset:64
	s_waitcnt vmcnt(16)
;     __device__ __forceinline__ void operator()(const f32x4 (&acc)[2][2][4][2], const Unit& u, int wr, int wc, int fr, int fq) const {
;     ...
;                 for (int bj = 0; bj < 2; ++bj) { const size_t c = (size_t)(row0 + ai * HALF + (mh + m) * 16) * 1024 + col0 + bj * 32;
;                     if (xin) { rh[m][bj] = __builtin_bit_cast(u32x4, *(const f32x4*)(xin + c)); rl[m][bj] = __builtin_bit_cast(u32x4, *(const f32x4*)(xin + c + 4)); }
;                     else { rh[m][bj] = *(const u32x4*)(hi + c); rl[m][bj] = *(const u32x4*)(lo_in + c); } }
; #pragma unroll
;             for (int m = 0; m < 2; ++m) { const int r = row0 + ai * HALF + (mh + m) * 16; float s = 0.f;
; #pragma unroll
;                 for (int bj = 0; bj < 2; ++bj) { const size_t c = (size_t)r * 1024 + col0 + bj * 32; const u32x4 h = rh[m][bj], l = rl[m][bj]; f32x4 b0, b1;
;                     if (xin) { b0 = __builtin_bit_cast(f32x4, h); b1 = __builtin_bit_cast(f32x4, l); }
;                     else { b0 = (f32x4){__uint_as_float(h.x << 16) + __uint_as_float(l.x << 16), __uint_as_float(h.x & 0xffff0000u) + __uint_as_float(l.x & 0xffff0000u),
;                                         __uint_as_float(h.y << 16) + __uint_as_float(l.y << 16), __uint_as_float(h.y & 0xffff0000u) + __uint_as_float(l.y & 0xffff0000u)};
;                            b1 = (f32x4){__uint_as_float(h.z << 16) + __uint_as_float(l.z << 16), __uint_as_float(h.z & 0xffff0000u) + __uint_as_float(l.z & 0xffff0000u),
;                                         __uint_as_float(h.w << 16) + __uint_as_float(l.w << 16), __uint_as_float(h.w & 0xffff0000u) + __uint_as_float(l.w & 0xffff0000u)}; }
;                     const f32x4 v0 = b0 + acc[ai][bj][mh + m][0] * scale + bv[bj][0], v1 = b1 + acc[ai][bj][mh + m][1] * scale + bv[bj][1];
;                     if (fout) { *(f32x4*)(fout + c) = v0; *(f32x4*)(fout + c + 4) = v1; }
;                     else { const unsigned h0 = pk2(v0[0], v0[1]), h1 = pk2(v0[2], v0[3]), h2 = pk2(v1[0], v1[1]), h3 = pk2(v1[2], v1[3]);
;                         const unsigned l0 = pk2(v0[0] - __uint_as_float(h0 << 16), v0[1] - __uint_as_float(h0 & 0xffff0000u)), l1 = pk2(v0[2] - __uint_as_float(h1 << 16), v0[3] - __uint_as_float(h1 & 0xffff0000u)),
	v_lshlrev_b32_e32 v218, 16, v84
	v_and_b32_e32 v219, 0xffff0000, v84
	v_lshlrev_b32_e32 v220, 16, v88
	v_and_b32_e32 v221, 0xffff0000, v88
	v_pk_add_f32 v[218:219], v[220:221], v[218:219]
	s_nop 0
	v_pk_fma_f32 v[32:33], s[20:21], v[32:33], v[218:219]
	v_lshlrev_b32_e32 v222, 16, v85
	v_and_b32_e32 v223, 0xffff0000, v85
	v_lshlrev_b32_e32 v250, 16, v89
	v_and_b32_e32 v251, 0xffff0000, v89
	v_pk_add_f32 v[222:223], v[250:251], v[222:223]
	s_nop 0
	v_pk_fma_f32 v[34:35], s[20:21], v[34:35], v[222:223]
	v_lshlrev_b32_e32 v218, 16, v86
	v_and_b32_e32 v219, 0xffff0000, v86
	v_lshlrev_b32_e32 v220, 16, v90
	v_and_b32_e32 v221, 0xffff0000, v90
	v_pk_add_f32 v[218:219], v[220:221], v[218:219]
	s_nop 0
	v_pk_fma_f32 v[28:29], s[20:21], v[28:29], v[218:219]
	v_lshlrev_b32_e32 v222, 16, v87
	v_and_b32_e32 v223, 0xffff0000, v87
	v_lshlrev_b32_e32 v250, 16, v91
	v_and_b32_e32 v251, 0xffff0000, v91
	v_pk_add_f32 v[222:223], v[250:251], v[222:223]
	s_nop 0
	v_pk_fma_f32 v[30:31], s[20:21], v[30:31], v[222:223]
	v_pk_add_f32 v[32:33], v[56:57], v[32:33]
	v_pk_add_f32 v[34:35], v[58:59], v[34:35]
	v_pk_add_f32 v[28:29], v[48:49], v[28:29]
	v_pk_add_f32 v[30:31], v[50:51], v[30:31]
	v_mul_f32_e32 v247, v32, v32
	v_mul_f32_e32 v249, v34, v34
	v_fmac_f32_e32 v247, v33, v33
	v_fmac_f32_e32 v249, v35, v35
	v_mul_f32_e32 v252, v28, v28
	v_add_f32_e32 v247, v247, v249
	v_mul_f32_e32 v249, v30, v30
	v_fmac_f32_e32 v252, v29, v29
	v_fmac_f32_e32 v249, v31, v31
	v_add_f32_e32 v252, v252, v249
	v_add_f32_e32 v247, v247, v252
	v_mov_b32_e32 v153, v247
	v_cvt_pk_bf16_f32 v84, v32, v33
	v_lshlrev_b32_e32 v218, 16, v84
	v_and_b32_e32 v219, 0xffff0000, v84
	v_pk_add_f32 v[32:33], v[32:33], v[218:219] neg_lo:[0,1] neg_hi:[0,1]
	s_nop 0
	v_cvt_pk_bf16_f32 v88, v32, v33
	v_cvt_pk_bf16_f32 v85, v34, v35
	v_lshlrev_b32_e32 v222, 16, v85
	v_and_b32_e32 v223, 0xffff0000, v85
	v_pk_add_f32 v[34:35], v[34:35], v[222:223] neg_lo:[0,1] neg_hi:[0,1]
	s_nop 0
	v_cvt_pk_bf16_f32 v89, v34, v35
	v_cvt_pk_bf16_f32 v86, v28, v29
	v_lshlrev_b32_e32 v218, 16, v86
	v_and_b32_e32 v219, 0xffff0000, v86
	v_pk_add_f32 v[28:29], v[28:29], v[218:219] neg_lo:[0,1] neg_hi:[0,1]
	s_nop 0
	v_cvt_pk_bf16_f32 v90, v28, v29
	v_cvt_pk_bf16_f32 v87, v30, v31
	v_lshlrev_b32_e32 v222, 16, v87
	v_and_b32_e32 v223, 0xffff0000, v87
	v_pk_add_f32 v[30:31], v[30:31], v[222:223] neg_lo:[0,1] neg_hi:[0,1]
	s_nop 0
	v_cvt_pk_bf16_f32 v91, v30, v31
	v_lshlrev_b32_e32 v218, 16, v92
	v_and_b32_e32 v219, 0xffff0000, v92
	v_lshlrev_b32_e32 v220, 16, v96
	v_and_b32_e32 v221, 0xffff0000, v96
	v_pk_add_f32 v[218:219], v[220:221], v[218:219]
	s_nop 0
	v_pk_fma_f32 v[24:25], s[20:21], v[24:25], v[218:219]
	v_lshlrev_b32_e32 v222, 16, v93
	v_and_b32_e32 v223, 0xffff0000, v93
	v_lshlrev_b32_e32 v250, 16, v97
	v_and_b32_e32 v251, 0xffff0000, v97
	v_pk_add_f32 v[222:223], v[250:251], v[222:223]
	s_nop 0
	v_pk_fma_f32 v[26:27], s[20:21], v[26:27], v[222:223]
	v_lshlrev_b32_e32 v218, 16, v94
	v_and_b32_e32 v219, 0xffff0000, v94
	v_lshlrev_b32_e32 v220, 16, v98
	v_and_b32_e32 v221, 0xffff0000, v98
	v_pk_add_f32 v[218:219], v[220:221], v[218:219]
	s_nop 0
	v_pk_fma_f32 v[20:21], s[20:21], v[20:21], v[218:219]
	v_lshlrev_b32_e32 v222, 16, v95
	v_and_b32_e32 v223, 0xffff0000, v95
	v_lshlrev_b32_e32 v250, 16, v99
	v_and_b32_e32 v251, 0xffff0000, v99
	v_pk_add_f32 v[222:223], v[250:251], v[222:223]
	s_nop 0
	v_pk_fma_f32 v[22:23], s[20:21], v[22:23], v[222:223]
	v_pk_add_f32 v[24:25], v[40:41], v[24:25]
	v_pk_add_f32 v[26:27], v[42:43], v[26:27]
	v_pk_add_f32 v[20:21], v[36:37], v[20:21]
	v_pk_add_f32 v[22:23], v[38:39], v[22:23]
	v_mul_f32_e32 v247, v24, v24
	v_mul_f32_e32 v249, v26, v26
	v_fmac_f32_e32 v247, v25, v25
	v_fmac_f32_e32 v249, v27, v27
	v_mul_f32_e32 v252, v20, v20
	v_add_f32_e32 v247, v247, v249
	v_mul_f32_e32 v249, v22, v22
	v_fmac_f32_e32 v252, v21, v21
	v_fmac_f32_e32 v249, v23, v23
	v_add_f32_e32 v252, v252, v249
	v_add_f32_e32 v247, v247, v252
	v_add_f32_e32 v153, v153, v247
	v_cvt_pk_bf16_f32 v92, v24, v25
	v_lshlrev_b32_e32 v218, 16, v92
	v_and_b32_e32 v219, 0xffff0000, v92
	v_pk_add_f32 v[24:25], v[24:25], v[218:219] neg_lo:[0,1] neg_hi:[0,1]
	s_nop 0
	v_cvt_pk_bf16_f32 v96, v24, v25
	v_cvt_pk_bf16_f32 v93, v26, v27
	v_lshlrev_b32_e32 v222, 16, v93
	v_and_b32_e32 v223, 0xffff0000, v93
	v_pk_add_f32 v[26:27], v[26:27], v[222:223] neg_lo:[0,1] neg_hi:[0,1]
	s_nop 0
	v_cvt_pk_bf16_f32 v97, v26, v27
	v_cvt_pk_bf16_f32 v94, v20, v21
	v_lshlrev_b32_e32 v218, 16, v94
	v_and_b32_e32 v219, 0xffff0000, v94
	v_pk_add_f32 v[20:21], v[20:21], v[218:219] neg_lo:[0,1] neg_hi:[0,1]
	s_nop 0
	v_cvt_pk_bf16_f32 v98, v20, v21
	v_cvt_pk_bf16_f32 v95, v22, v23
	v_lshlrev_b32_e32 v222, 16, v95
	v_and_b32_e32 v223, 0xffff0000, v95
	v_pk_add_f32 v[22:23], v[22:23], v[222:223] neg_lo:[0,1] neg_hi:[0,1]
	s_nop 0
	v_cvt_pk_bf16_f32 v99, v22, v23
	v_add_u32_e32 v245, 0x50000, v212
	global_store_dwordx4 v245, v[84:87], s[78:79]
	global_store_dwordx4 v245, v[92:95], s[78:79] offset:64
	global_store_dwordx4 v245, v[88:91], s[28:29]
	global_store_dwordx4 v245, v[96:99], s[28:29] offset:64
	s_waitcnt vmcnt(12)
;     __device__ __forceinline__ void operator()(const f32x4 (&acc)[2][2][4][2], const Unit& u, int wr, int wc, int fr, int fq) const {
;     ...
;                 for (int bj = 0; bj < 2; ++bj) { const size_t c = (size_t)(row0 + ai * HALF + (mh + m) * 16) * 1024 + col0 + bj * 32;
;                     if (xin) { rh[m][bj] = __builtin_bit_cast(u32x4, *(const f32x4*)(xin + c)); rl[m][bj] = __builtin_bit_cast(u32x4, *(const f32x4*)(xin + c + 4)); }
;                     else { rh[m][bj] = *(const u32x4*)(hi + c); rl[m][bj] = *(const u32x4*)(lo_in + c); } }
; #pragma unroll
;             for (int m = 0; m < 2; ++m) { const int r = row0 + ai * HALF + (mh + m) * 16; float s = 0.f;
; #pragma unroll
;                 for (int bj = 0; bj < 2; ++bj) { const size_t c = (size_t)r * 1024 + col0 + bj * 32; const u32x4 h = rh[m][bj], l = rl[m][bj]; f32x4 b0, b1;
;                     if (xin) { b0 = __builtin_bit_cast(f32x4, h); b1 = __builtin_bit_cast(f32x4, l); }
;                     else { b0 = (f32x4){__uint_as_float(h.x << 16) + __uint_as_float(l.x << 16), __uint_as_float(h.x & 0xffff0000u) + __uint_as_float(l.x & 0xffff0000u),
;                                         __uint_as_float(h.y << 16) + __uint_as_float(l.y << 16), __uint_as_float(h.y & 0xffff0000u) + __uint_as_float(l.y & 0xffff0000u)};
;                            b1 = (f32x4){__uint_as_float(h.z << 16) + __uint_as_float(l.z << 16), __uint_as_float(h.z & 0xffff0000u) + __uint_as_float(l.z & 0xffff0000u),
;                                         __uint_as_float(h.w << 16) + __uint_as_float(l.w << 16), __uint_as_float(h.w & 0xffff0000u) + __uint_as_float(l.w & 0xffff0000u)}; }
;                     const f32x4 v0 = b0 + acc[ai][bj][mh + m][0] * scale + bv[bj][0], v1 = b1 + acc[ai][bj][mh + m][1] * scale + bv[bj][1];
;                     if (fout) { *(f32x4*)(fout + c) = v0; *(f32x4*)(fout + c + 4) = v1; }
;                     else { const unsigned h0 = pk2(v0[0], v0[1]), h1 = pk2(v0[2], v0[3]), h2 = pk2(v1[0], v1[1]), h3 = pk2(v1[2], v1[3]);
;                         const unsigned l0 = pk2(v0[0] - __uint_as_float(h0 << 16), v0[1] - __uint_as_float(h0 & 0xffff0000u)), l1 = pk2(v0[2] - __uint_as_float(h1 << 16), v0[3] - __uint_as_float(h1 & 0xffff0000u)),
	v_lshlrev_b32_e32 v218, 16, v68
	v_and_b32_e32 v219, 0xffff0000, v68
	v_lshlrev_b32_e32 v220, 16, v72
	v_and_b32_e32 v221, 0xffff0000, v72
	v_pk_add_f32 v[218:219], v[220:221], v[218:219]
	s_nop 0
	v_pk_fma_f32 v[16:17], s[20:21], v[16:17], v[218:219]
	v_lshlrev_b32_e32 v222, 16, v69
	v_and_b32_e32 v223, 0xffff0000, v69
	v_lshlrev_b32_e32 v250, 16, v73
	v_and_b32_e32 v251, 0xffff0000, v73
	v_pk_add_f32 v[222:223], v[250:251], v[222:223]
	s_nop 0
	v_pk_fma_f32 v[18:19], s[20:21], v[18:19], v[222:223]
	v_lshlrev_b32_e32 v218, 16, v70
	v_and_b32_e32 v219, 0xffff0000, v70
	v_lshlrev_b32_e32 v220, 16, v74
	v_and_b32_e32 v221, 0xffff0000, v74
	v_pk_add_f32 v[218:219], v[220:221], v[218:219]
	s_nop 0
	v_pk_fma_f32 v[12:13], s[20:21], v[12:13], v[218:219]
	v_lshlrev_b32_e32 v222, 16, v71
	v_and_b32_e32 v223, 0xffff0000, v71
	v_lshlrev_b32_e32 v250, 16, v75
	v_and_b32_e32 v251, 0xffff0000, v75
	v_pk_add_f32 v[222:223], v[250:251], v[222:223]
	s_nop 0
	v_pk_fma_f32 v[14:15], s[20:21], v[14:15], v[222:223]
	v_pk_add_f32 v[16:17], v[56:57], v[16:17]
	v_pk_add_f32 v[18:19], v[58:59], v[18:19]
	v_pk_add_f32 v[12:13], v[48:49], v[12:13]
	v_pk_add_f32 v[14:15], v[50:51], v[14:15]
	v_mul_f32_e32 v247, v16, v16
	v_mul_f32_e32 v249, v18, v18
	v_fmac_f32_e32 v247, v17, v17
	v_fmac_f32_e32 v249, v19, v19
	v_mul_f32_e32 v252, v12, v12
	v_add_f32_e32 v247, v247, v249
	v_mul_f32_e32 v249, v14, v14
	v_fmac_f32_e32 v252, v13, v13
	v_fmac_f32_e32 v249, v15, v15
	v_add_f32_e32 v252, v252, v249
	v_add_f32_e32 v247, v247, v252
	v_mov_b32_e32 v154, v247
	v_cvt_pk_bf16_f32 v68, v16, v17
	v_lshlrev_b32_e32 v218, 16, v68
	v_and_b32_e32 v219, 0xffff0000, v68
	v_pk_add_f32 v[16:17], v[16:17], v[218:219] neg_lo:[0,1] neg_hi:[0,1]
	s_nop 0
	v_cvt_pk_bf16_f32 v72, v16, v17
	v_cvt_pk_bf16_f32 v69, v18, v19
	v_lshlrev_b32_e32 v222, 16, v69
	v_and_b32_e32 v223, 0xffff0000, v69
	v_pk_add_f32 v[18:19], v[18:19], v[222:223] neg_lo:[0,1] neg_hi:[0,1]
	s_nop 0
	v_cvt_pk_bf16_f32 v73, v18, v19
	v_cvt_pk_bf16_f32 v70, v12, v13
	v_lshlrev_b32_e32 v218, 16, v70
	v_and_b32_e32 v219, 0xffff0000, v70
	v_pk_add_f32 v[12:13], v[12:13], v[218:219] neg_lo:[0,1] neg_hi:[0,1]
	s_nop 0
	v_cvt_pk_bf16_f32 v74, v12, v13
	v_cvt_pk_bf16_f32 v71, v14, v15
	v_lshlrev_b32_e32 v222, 16, v71
	v_and_b32_e32 v223, 0xffff0000, v71
	v_pk_add_f32 v[14:15], v[14:15], v[222:223] neg_lo:[0,1] neg_hi:[0,1]
	s_nop 0
	v_cvt_pk_bf16_f32 v75, v14, v15
	v_lshlrev_b32_e32 v218, 16, v76
	v_and_b32_e32 v219, 0xffff0000, v76
	v_lshlrev_b32_e32 v220, 16, v80
	v_and_b32_e32 v221, 0xffff0000, v80
	v_pk_add_f32 v[218:219], v[220:221], v[218:219]
	s_nop 0
	v_pk_fma_f32 v[8:9], s[20:21], v[8:9], v[218:219]
	v_lshlrev_b32_e32 v222, 16, v77
	v_and_b32_e32 v223, 0xffff0000, v77
	v_lshlrev_b32_e32 v250, 16, v81
	v_and_b32_e32 v251, 0xffff0000, v81
	v_pk_add_f32 v[222:223], v[250:251], v[222:223]
	s_nop 0
	v_pk_fma_f32 v[10:11], s[20:21], v[10:11], v[222:223]
	v_lshlrev_b32_e32 v218, 16, v78
	v_and_b32_e32 v219, 0xffff0000, v78
	v_lshlrev_b32_e32 v220, 16, v82
	v_and_b32_e32 v221, 0xffff0000, v82
	v_pk_add_f32 v[218:219], v[220:221], v[218:219]
	s_nop 0
	v_pk_fma_f32 v[4:5], s[20:21], v[4:5], v[218:219]
	v_lshlrev_b32_e32 v222, 16, v79
	v_and_b32_e32 v223, 0xffff0000, v79
	v_lshlrev_b32_e32 v250, 16, v83
	v_and_b32_e32 v251, 0xffff0000, v83
	v_pk_add_f32 v[222:223], v[250:251], v[222:223]
	s_nop 0
	v_pk_fma_f32 v[6:7], s[20:21], v[6:7], v[222:223]
	v_pk_add_f32 v[8:9], v[40:41], v[8:9]
	v_pk_add_f32 v[10:11], v[42:43], v[10:11]
	v_pk_add_f32 v[4:5], v[36:37], v[4:5]
	v_pk_add_f32 v[6:7], v[38:39], v[6:7]
	v_mul_f32_e32 v247, v8, v8
	v_mul_f32_e32 v249, v10, v10
	v_fmac_f32_e32 v247, v9, v9
	v_fmac_f32_e32 v249, v11, v11
	v_mul_f32_e32 v252, v4, v4
	v_add_f32_e32 v247, v247, v249
	v_mul_f32_e32 v249, v6, v6
	v_fmac_f32_e32 v252, v5, v5
	v_fmac_f32_e32 v249, v7, v7
	v_add_f32_e32 v252, v252, v249
	v_add_f32_e32 v247, v247, v252
	v_add_f32_e32 v154, v154, v247
	v_cvt_pk_bf16_f32 v76, v8, v9
	v_lshlrev_b32_e32 v218, 16, v76
	v_and_b32_e32 v219, 0xffff0000, v76
	v_pk_add_f32 v[8:9], v[8:9], v[218:219] neg_lo:[0,1] neg_hi:[0,1]
	s_nop 0
	v_cvt_pk_bf16_f32 v80, v8, v9
	v_cvt_pk_bf16_f32 v77, v10, v11
	v_lshlrev_b32_e32 v222, 16, v77
	v_and_b32_e32 v223, 0xffff0000, v77
	v_pk_add_f32 v[10:11], v[10:11], v[222:223] neg_lo:[0,1] neg_hi:[0,1]
	s_nop 0
	v_cvt_pk_bf16_f32 v81, v10, v11
	v_cvt_pk_bf16_f32 v78, v4, v5
	v_lshlrev_b32_e32 v218, 16, v78
	v_and_b32_e32 v219, 0xffff0000, v78
	v_pk_add_f32 v[4:5], v[4:5], v[218:219] neg_lo:[0,1] neg_hi:[0,1]
	s_nop 0
	v_cvt_pk_bf16_f32 v82, v4, v5
	v_cvt_pk_bf16_f32 v79, v6, v7
	v_lshlrev_b32_e32 v222, 16, v79
	v_and_b32_e32 v223, 0xffff0000, v79
	v_pk_add_f32 v[6:7], v[6:7], v[222:223] neg_lo:[0,1] neg_hi:[0,1]
	s_nop 0
	v_cvt_pk_bf16_f32 v83, v6, v7
	v_add_u32_e32 v245, 0x58000, v212
	global_store_dwordx4 v245, v[68:71], s[78:79]
	global_store_dwordx4 v245, v[76:79], s[78:79] offset:64
	global_store_dwordx4 v245, v[72:75], s[28:29]
	global_store_dwordx4 v245, v[80:83], s[28:29] offset:64
	v_xor_b32_e32 v155, 16, v236
	v_xor_b32_e32 v156, 32, v236
	v_lshlrev_b32_e32 v155, 2, v155
	v_lshlrev_b32_e32 v156, 2, v156
	ds_bpermute_b32 v157, v155, v213
	ds_bpermute_b32 v158, v155, v148
	ds_bpermute_b32 v159, v155, v149
	ds_bpermute_b32 v160, v155, v150
	ds_bpermute_b32 v161, v155, v151
	ds_bpermute_b32 v162, v155, v152
	ds_bpermute_b32 v163, v155, v153
	ds_bpermute_b32 v164, v155, v154
	s_waitcnt lgkmcnt(7)
;     __device__ __forceinline__ void operator()(const f32x4 (&acc)[2][2][4][2], const Unit& u, int wr, int wc, int fr, int fq) const {
;     ...
;                 s += __shfl_xor(s, 16); s += __shfl_xor(s, 32);
;                 if (fq == 0) ssn[(size_t)r * 16 + u.pn * 4 + wc] = s; }
	v_add_f32_e32 v213, v213, v157
	ds_bpermute_b32 v157, v156, v213
	s_waitcnt lgkmcnt(7)
	v_add_f32_e32 v148, v148, v158
	ds_bpermute_b32 v158, v156, v148
	s_waitcnt lgkmcnt(7)
	v_add_f32_e32 v149, v149, v159
	ds_bpermute_b32 v159, v156, v149
	s_waitcnt lgkmcnt(7)
	v_add_f32_e32 v150, v150, v160
	ds_bpermute_b32 v160, v156, v150
	s_waitcnt lgkmcnt(7)
	v_add_f32_e32 v151, v151, v161
	ds_bpermute_b32 v161, v156, v151
	s_waitcnt lgkmcnt(7)
	v_add_f32_e32 v152, v152, v162
	ds_bpermute_b32 v162, v156, v152
	s_waitcnt lgkmcnt(7)
	v_add_f32_e32 v153, v153, v163
	ds_bpermute_b32 v163, v156, v153
	s_waitcnt lgkmcnt(7)
	v_add_f32_e32 v154, v154, v164
	ds_bpermute_b32 v164, v156, v154
	s_lshl_b32 s46, s80, 4
	s_lshl_b32 s47, s72, 2
	s_add_u32 s46, s46, s47
	v_lshl_add_u32 v245, s81, 8, v187
	v_lshlrev_b32_e32 v245, 6, v245
	v_add_u32_e32 v245, s46, v245
	s_waitcnt lgkmcnt(7)
	v_add_f32_e32 v213, v213, v157
	s_waitcnt lgkmcnt(6)
	v_add_f32_e32 v148, v148, v158
	s_waitcnt lgkmcnt(5)
	v_add_f32_e32 v149, v149, v159
	s_waitcnt lgkmcnt(4)
	v_add_f32_e32 v150, v150, v160
	s_waitcnt lgkmcnt(3)
	v_add_f32_e32 v151, v151, v161
	s_waitcnt lgkmcnt(2)
	v_add_f32_e32 v152, v152, v162
	s_waitcnt lgkmcnt(1)
	v_add_f32_e32 v153, v153, v163
	s_waitcnt lgkmcnt(0)
	v_add_f32_e32 v154, v154, v164
	s_and_saveexec_b64 s[2:3], s[6:7]
	v_add_u32_e32 v217, 0x0, v245
	global_store_dword v217, v213, s[4:5]
	v_add_u32_e32 v217, 0x400, v245
	global_store_dword v217, v148, s[4:5]
	v_add_u32_e32 v217, 0x800, v245
	global_store_dword v217, v149, s[4:5]
	v_add_u32_e32 v217, 0xc00, v245
	global_store_dword v217, v150, s[4:5]
	v_add_u32_e32 v217, 0x2000, v245
	global_store_dword v217, v151, s[4:5]
	v_add_u32_e32 v217, 0x2400, v245
	global_store_dword v217, v152, s[4:5]
	v_add_u32_e32 v217, 0x2800, v245
	global_store_dword v217, v153, s[4:5]
	v_add_u32_e32 v217, 0x2c00, v245
	global_store_dword v217, v154, s[4:5]
	s_branch .LBB0_516
